# MLA attention PV: V-fragment LDS reads through a 5-deep ring of the dead K-fragment quads with counted lgkmcnt waits (was 1 MFMA ahead in 2 quads)
# speedup vs baseline: 1.0081x; 1.0042x over previous
.LBB0_566:
	s_and_saveexec_b64 s[22:23], vcc
	s_cbranch_execz .LBB0_555
	ds_read_b128 v[196:199], v188
	ds_read_b128 v[202:205], v188 offset:32
	ds_read_b128 v[206:209], v188 offset:64
	ds_read_b128 v[210:213], v188 offset:96
	ds_read_b128 v[220:223], v188 offset:128
	ds_read_b128 v[224:227], v188 offset:160
	ds_read_b128 v[2:5], v188 offset:192
	ds_read_b128 v[6:9], v188 offset:224
	s_waitcnt lgkmcnt(7)
	v_mfma_f32_32x32x16_bf16 v[96:111], v[196:199], v[148:151], 0
	ds_read_b128 v[196:199], v188 offset:256
	s_waitcnt lgkmcnt(7)
	v_mfma_f32_32x32x16_bf16 v[96:111], v[202:205], v[144:147], v[96:111]
	ds_read_b128 v[202:205], v188 offset:288
	s_waitcnt lgkmcnt(7)
	v_mfma_f32_32x32x16_bf16 v[96:111], v[206:209], v[140:143], v[96:111]
	ds_read_b128 v[206:209], v188 offset:10752
	s_waitcnt lgkmcnt(7)
	v_mfma_f32_32x32x16_bf16 v[96:111], v[210:213], v[136:139], v[96:111]
	ds_read_b128 v[210:213], v188 offset:10784
	s_waitcnt lgkmcnt(7)
	v_mfma_f32_32x32x16_bf16 v[96:111], v[220:223], v[132:135], v[96:111]
	ds_read_b128 v[220:223], v188 offset:10816
	s_waitcnt lgkmcnt(7)
	v_mfma_f32_32x32x16_bf16 v[96:111], v[224:227], v[128:131], v[96:111]
	ds_read_b128 v[224:227], v188 offset:10848
	s_waitcnt lgkmcnt(7)
	v_mfma_f32_32x32x16_bf16 v[96:111], v[2:5], v[124:127], v[96:111]
	ds_read_b128 v[2:5], v188 offset:10880
	s_waitcnt lgkmcnt(7)
	v_mfma_f32_32x32x16_bf16 v[96:111], v[6:9], v[120:123], v[96:111]
	ds_read_b128 v[6:9], v188 offset:10912
	s_waitcnt lgkmcnt(7)
	v_mfma_f32_32x32x16_bf16 v[96:111], v[196:199], v[116:119], v[96:111]
	ds_read_b128 v[196:199], v188 offset:10944
	s_waitcnt lgkmcnt(7)
	v_mfma_f32_32x32x16_bf16 v[96:111], v[202:205], v[112:115], v[96:111]
	ds_read_b128 v[202:205], v188 offset:10976
	s_waitcnt lgkmcnt(7)
	v_mfma_f32_32x32x16_bf16 v[80:95], v[206:209], v[148:151], 0
	ds_read_b128 v[206:209], v188 offset:11008
	s_waitcnt lgkmcnt(7)
	v_mfma_f32_32x32x16_bf16 v[80:95], v[210:213], v[144:147], v[80:95]
	ds_read_b128 v[210:213], v188 offset:11040
	s_waitcnt lgkmcnt(7)
	v_mfma_f32_32x32x16_bf16 v[80:95], v[220:223], v[140:143], v[80:95]
	s_waitcnt lgkmcnt(6)
	v_mfma_f32_32x32x16_bf16 v[80:95], v[224:227], v[136:139], v[80:95]
	s_waitcnt lgkmcnt(5)
	v_mfma_f32_32x32x16_bf16 v[80:95], v[2:5], v[132:135], v[80:95]
	s_waitcnt lgkmcnt(4)
	v_mfma_f32_32x32x16_bf16 v[80:95], v[6:9], v[128:131], v[80:95]
	s_waitcnt lgkmcnt(3)
	v_mfma_f32_32x32x16_bf16 v[80:95], v[196:199], v[124:127], v[80:95]
	v_max_f32_e32 v0, v97, v97
	v_max_f32_e32 v10, v96, v96
	v_max_f32_e32 v0, v10, v0
	v_max3_f32 v0, v0, v98, v99
	v_max3_f32 v0, v0, v100, v101
	v_max3_f32 v0, v0, v102, v103
	v_max3_f32 v0, v0, v104, v105
	v_max3_f32 v0, v0, v106, v107
	v_max3_f32 v0, v0, v108, v109
	v_max3_f32 v0, v0, v110, v111
	v_and_b32_e32 v3, 64, v218
	v_xor_b32_e32 v2, 32, v218
	v_add_u32_e32 v3, 64, v3
	v_cmp_lt_i32_e64 s[12:13], v2, v3
	s_nop 1
	v_cndmask_b32_e64 v2, v218, v2, s[12:13]
	s_waitcnt lgkmcnt(2)
	v_mfma_f32_32x32x16_bf16 v[80:95], v[202:205], v[120:123], v[80:95]
	s_waitcnt lgkmcnt(1)
	v_mfma_f32_32x32x16_bf16 v[80:95], v[206:209], v[116:119], v[80:95]
	s_waitcnt lgkmcnt(0)
	v_mfma_f32_32x32x16_bf16 v[80:95], v[210:213], v[112:115], v[80:95]
	v_lshlrev_b32_e32 v2, 2, v2
	s_nop 10
	v_max3_f32 v0, v0, v80, v81
	v_max3_f32 v0, v0, v82, v83
	v_max3_f32 v0, v0, v84, v85
	v_max3_f32 v0, v0, v86, v87
	v_max3_f32 v0, v0, v88, v89
	v_max3_f32 v0, v0, v90, v91
	v_max3_f32 v0, v0, v92, v93
	v_max3_f32 v0, v0, v94, v95
	ds_bpermute_b32 v2, v2, v0
	s_waitcnt lgkmcnt(0)
	v_add_u32_e32 v224, 0x5000, v194
	v_add_u32_e32 v225, 0x6000, v194
	v_add_u32_e32 v226, 0x7000, v194
	v_add_u32_e32 v227, 0x8000, v194
	ds_read2_b64 v[196:199], v224 offset0:128 offset1:130
	ds_read2_b64 v[202:205], v225 offset0:160 offset1:162
	ds_read2_b64 v[206:209], v226 offset0:192 offset1:194
	ds_read2_b64 v[210:213], v227 offset0:224 offset1:226
	ds_read2_b64 v[220:223], v224 offset0:132 offset1:134
	v_max3_f32 v0, v195, v0, v2
	v_sub_f32 v4, v97, v0
	v_sub_f32 v3, v96, v0
	v_sub_f32 v5, v100, v0
	v_sub_f32_e32 v2, v195, v0
	v_exp_f32_e32 v8, v4
	v_sub_f32 v4, v98, v0
	v_exp_f32_e32 v3, v3
	v_exp_f32_e32 v9, v4
	v_sub_f32 v4, v99, v0
	v_exp_f32_e32 v11, v5
	v_exp_f32_e32 v10, v4
	v_add_f32 v4, v1, v3
	v_sub_f32 v5, v101, v0
	v_exp_f32_e32 v2, v2
	v_add_f32 v4, v4, v8
	v_exp_f32_e32 v12, v5
	v_add_f32 v4, v4, v9
	v_sub_f32 v5, v102, v0
	v_cvt_pk_bf16_f32 v8, v3, v8
	v_add_f32 v4, v4, v10
	v_exp_f32_e32 v13, v5
	v_add_f32 v4, v4, v11
	v_sub_f32 v5, v103, v0
	v_add_f32 v4, v4, v12
	v_exp_f32_e32 v14, v5
	v_add_f32 v4, v4, v13
	v_cvt_pk_bf16_f32 v9, v9, v10
	v_add_f32 v96, v4, v14
	v_sub_f32 v4, v104, v0
	v_exp_f32_e32 v97, v4
	v_sub_f32 v4, v105, v0
	v_cvt_pk_bf16_f32 v10, v11, v12
	v_exp_f32_e32 v98, v4
	v_sub_f32 v4, v106, v0
	v_cvt_pk_bf16_f32 v11, v13, v14
	v_exp_f32_e32 v99, v4
	v_sub_f32 v4, v107, v0
	v_exp_f32_e32 v100, v4
	v_sub_f32 v4, v108, v0
	v_pk_mul_f32 v[64:65], v[64:65], v[2:3] op_sel_hi:[1,0]
	v_pk_mul_f32 v[66:67], v[66:67], v[2:3] op_sel_hi:[1,0]
	v_pk_mul_f32 v[68:69], v[68:69], v[2:3] op_sel_hi:[1,0]
	s_nop 0
	v_exp_f32_e32 v101, v4
	v_sub_f32 v4, v109, v0
	v_pk_mul_f32 v[70:71], v[70:71], v[2:3] op_sel_hi:[1,0]
	v_pk_mul_f32 v[72:73], v[72:73], v[2:3] op_sel_hi:[1,0]
	s_nop 0
	v_exp_f32_e32 v102, v4
	v_sub_f32 v4, v110, v0
	v_pk_mul_f32 v[74:75], v[74:75], v[2:3] op_sel_hi:[1,0]
	v_pk_mul_f32 v[76:77], v[76:77], v[2:3] op_sel_hi:[1,0]
	v_pk_mul_f32 v[78:79], v[78:79], v[2:3] op_sel_hi:[1,0]
	s_nop 0
	v_exp_f32_e32 v103, v4
	s_waitcnt lgkmcnt(4)
	v_mfma_f32_32x32x16_bf16 v[64:79], v[196:199], v[8:11], v[64:79]
	ds_read2_b64 v[196:199], v225 offset0:164 offset1:166
	v_pk_mul_f32 v[48:49], v[48:49], v[2:3] op_sel_hi:[1,0]
	v_pk_mul_f32 v[50:51], v[50:51], v[2:3] op_sel_hi:[1,0]
	v_pk_mul_f32 v[52:53], v[52:53], v[2:3] op_sel_hi:[1,0]
	v_pk_mul_f32 v[54:55], v[54:55], v[2:3] op_sel_hi:[1,0]
	v_pk_mul_f32 v[56:57], v[56:57], v[2:3] op_sel_hi:[1,0]
	v_pk_mul_f32 v[58:59], v[58:59], v[2:3] op_sel_hi:[1,0]
	v_pk_mul_f32 v[60:61], v[60:61], v[2:3] op_sel_hi:[1,0]
	v_pk_mul_f32 v[62:63], v[62:63], v[2:3] op_sel_hi:[1,0]
	s_waitcnt lgkmcnt(4)
	v_mfma_f32_32x32x16_bf16 v[48:63], v[202:205], v[8:11], v[48:63]
	ds_read2_b64 v[202:205], v226 offset0:196 offset1:198
	v_pk_mul_f32 v[32:33], v[32:33], v[2:3] op_sel_hi:[1,0]
	v_pk_mul_f32 v[34:35], v[34:35], v[2:3] op_sel_hi:[1,0]
	v_pk_mul_f32 v[36:37], v[36:37], v[2:3] op_sel_hi:[1,0]
	v_pk_mul_f32 v[38:39], v[38:39], v[2:3] op_sel_hi:[1,0]
	v_pk_mul_f32 v[40:41], v[40:41], v[2:3] op_sel_hi:[1,0]
	v_pk_mul_f32 v[42:43], v[42:43], v[2:3] op_sel_hi:[1,0]
	v_pk_mul_f32 v[44:45], v[44:45], v[2:3] op_sel_hi:[1,0]
	v_pk_mul_f32 v[46:47], v[46:47], v[2:3] op_sel_hi:[1,0]
	v_pk_mul_f32 v[16:17], v[16:17], v[2:3] op_sel_hi:[1,0]
	v_pk_mul_f32 v[18:19], v[18:19], v[2:3] op_sel_hi:[1,0]
	v_pk_mul_f32 v[20:21], v[20:21], v[2:3] op_sel_hi:[1,0]
	s_waitcnt lgkmcnt(4)
	v_mfma_f32_32x32x16_bf16 v[32:47], v[206:209], v[8:11], v[32:47]
	ds_read2_b64 v[206:209], v227 offset0:228 offset1:230
	v_pk_mul_f32 v[22:23], v[22:23], v[2:3] op_sel_hi:[1,0]
	v_pk_mul_f32 v[24:25], v[24:25], v[2:3] op_sel_hi:[1,0]
	v_pk_mul_f32 v[26:27], v[26:27], v[2:3] op_sel_hi:[1,0]
	v_pk_mul_f32 v[28:29], v[28:29], v[2:3] op_sel_hi:[1,0]
	v_pk_mul_f32 v[30:31], v[30:31], v[2:3] op_sel_hi:[1,0]
	v_mov_b32_e32 v195, v0
	s_waitcnt lgkmcnt(4)
	v_mfma_f32_32x32x16_bf16 v[16:31], v[210:213], v[8:11], v[16:31]
	ds_read2_b64 v[210:213], v224 offset0:136 offset1:138
	v_sub_f32 v8, v111, v0
	v_cvt_pk_bf16_f32 v9, v99, v100
	v_exp_f32_e32 v107, v8
	v_cvt_pk_bf16_f32 v8, v97, v98
	v_cvt_pk_bf16_f32 v10, v101, v102
	v_cvt_pk_bf16_f32 v11, v103, v107
	s_nop 0
	s_waitcnt lgkmcnt(4)
	v_mfma_f32_32x32x16_bf16 v[64:79], v[220:223], v[8:11], v[64:79]
	ds_read2_b64 v[220:223], v225 offset0:168 offset1:170
	v_add_f32 v4, v96, v97
	s_nop 0
	v_add_f32 v4, v4, v98
	s_nop 0
	v_add_f32 v4, v4, v99
	s_nop 0
	v_add_f32 v96, v4, v100
	v_sub_f32 v4, v80, v0
	s_waitcnt lgkmcnt(4)
	v_mfma_f32_32x32x16_bf16 v[48:63], v[196:199], v[8:11], v[48:63]
	ds_read2_b64 v[196:199], v226 offset0:200 offset1:202
	v_exp_f32_e32 v80, v4
	v_sub_f32 v12, v81, v0
	s_nop 0
	v_exp_f32_e32 v81, v12
	v_sub_f32 v12, v82, v0
	s_nop 0
	v_exp_f32_e32 v82, v12
	v_sub_f32 v12, v83, v0
	s_waitcnt lgkmcnt(4)
	v_mfma_f32_32x32x16_bf16 v[32:47], v[202:205], v[8:11], v[32:47]
	ds_read2_b64 v[202:205], v227 offset0:232 offset1:234
	v_exp_f32_e32 v83, v12
	v_sub_f32 v4, v84, v0
	s_nop 0
	v_exp_f32_e32 v84, v4
	v_sub_f32 v4, v85, v0
	s_nop 0
	v_exp_f32_e32 v85, v4
	v_sub_f32 v4, v86, v0
	s_waitcnt lgkmcnt(4)
	v_mfma_f32_32x32x16_bf16 v[16:31], v[206:209], v[8:11], v[16:31]
	ds_read2_b64 v[206:209], v224 offset0:140 offset1:142
	v_exp_f32_e32 v86, v4
	v_sub_f32 v8, v87, v0
	v_exp_f32_e32 v87, v8
	v_cvt_pk_bf16_f32 v8, v80, v81
	v_cvt_pk_bf16_f32 v9, v82, v83
	v_cvt_pk_bf16_f32 v10, v84, v85
	v_cvt_pk_bf16_f32 v11, v86, v87
	s_nop 0
	s_waitcnt lgkmcnt(4)
	v_mfma_f32_32x32x16_bf16 v[64:79], v[210:213], v[8:11], v[64:79]
	ds_read2_b64 v[210:213], v225 offset0:172 offset1:174
	v_add_f32 v4, v96, v101
	s_nop 0
	v_add_f32 v4, v4, v102
	s_nop 0
	v_add_f32 v4, v4, v103
	s_nop 0
	v_add_f32 v96, v4, v107
	v_sub_f32 v4, v88, v0
	s_waitcnt lgkmcnt(4)
	v_mfma_f32_32x32x16_bf16 v[48:63], v[220:223], v[8:11], v[48:63]
	ds_read2_b64 v[220:223], v226 offset0:204 offset1:206
	v_exp_f32_e32 v88, v4
	v_sub_f32 v12, v89, v0
	s_nop 0
	v_exp_f32_e32 v89, v12
	v_sub_f32 v12, v90, v0
	s_nop 0
	v_exp_f32_e32 v90, v12
	v_sub_f32 v12, v91, v0
	s_waitcnt lgkmcnt(4)
	v_mfma_f32_32x32x16_bf16 v[32:47], v[196:199], v[8:11], v[32:47]
	ds_read2_b64 v[196:199], v227 offset0:236 offset1:238
	v_exp_f32_e32 v91, v12
	v_sub_f32 v4, v92, v0
	s_nop 0
	v_exp_f32_e32 v92, v4
	v_sub_f32 v4, v93, v0
	s_nop 0
	v_exp_f32_e32 v93, v4
	v_sub_f32 v4, v94, v0
	s_waitcnt lgkmcnt(4)
	v_mfma_f32_32x32x16_bf16 v[16:31], v[202:205], v[8:11], v[16:31]
	v_exp_f32_e32 v94, v4
	v_sub_f32 v8, v95, v0
	v_cvt_pk_bf16_f32 v9, v90, v91
	v_exp_f32_e32 v95, v8
	v_cvt_pk_bf16_f32 v8, v88, v89
	v_cvt_pk_bf16_f32 v10, v92, v93
	v_add_f32 v3, v96, v80
	v_cvt_pk_bf16_f32 v11, v94, v95
	v_add_f32 v3, v3, v81
	s_nop 0
	v_add_f32 v3, v3, v82
	s_waitcnt lgkmcnt(3)
	v_mfma_f32_32x32x16_bf16 v[64:79], v[206:209], v[8:11], v[64:79]
	v_add_f32 v3, v3, v83
	s_nop 0
	v_add_f32 v3, v3, v84
	s_nop 0
	v_add_f32 v3, v3, v85
	s_waitcnt lgkmcnt(2)
	v_mfma_f32_32x32x16_bf16 v[48:63], v[210:213], v[8:11], v[48:63]
	v_add_f32 v3, v3, v86
	s_nop 0
	v_add_f32 v3, v3, v87
	s_nop 0
	v_add_f32 v3, v3, v88
	s_nop 0
	v_add_f32 v3, v3, v89
	s_waitcnt lgkmcnt(1)
	v_mfma_f32_32x32x16_bf16 v[32:47], v[220:223], v[8:11], v[32:47]
	v_add_f32 v3, v3, v90
	s_nop 0
	v_add_f32 v3, v3, v91
	s_nop 0
	v_add_f32 v3, v3, v92
	s_nop 0
	v_add_f32 v3, v3, v93
	s_waitcnt lgkmcnt(0)
	v_mfma_f32_32x32x16_bf16 v[16:31], v[196:199], v[8:11], v[16:31]
	v_add_f32 v3, v3, v94
	s_nop 0
	v_add_f32 v3, v3, v95
	s_nop 0
	v_fmac_f32_e32 v3, v184, v2
	v_mov_b32_e32 v184, v3
	s_branch .LBB0_555

.LBB0_598:
	s_and_saveexec_b64 s[24:25], s[6:7]
	s_cbranch_execz .LBB0_587
	ds_read_b128 v[194:197], v185
	ds_read_b128 v[202:205], v185 offset:32
	ds_read_b128 v[206:209], v185 offset:64
	ds_read_b128 v[210:213], v185 offset:96
	ds_read_b128 v[220:223], v185 offset:128
	ds_read_b128 v[224:227], v185 offset:160
	ds_read_b128 v[2:5], v185 offset:192
	ds_read_b128 v[6:9], v185 offset:224
	s_waitcnt lgkmcnt(7)
	v_mfma_f32_32x32x16_bf16 v[96:111], v[194:197], v[148:151], 0
	ds_read_b128 v[194:197], v185 offset:256
	s_waitcnt lgkmcnt(7)
	v_mfma_f32_32x32x16_bf16 v[96:111], v[202:205], v[144:147], v[96:111]
	ds_read_b128 v[202:205], v185 offset:288
	s_waitcnt lgkmcnt(7)
	v_mfma_f32_32x32x16_bf16 v[96:111], v[206:209], v[140:143], v[96:111]
	ds_read_b128 v[206:209], v185 offset:10752
	s_waitcnt lgkmcnt(7)
	v_mfma_f32_32x32x16_bf16 v[96:111], v[210:213], v[136:139], v[96:111]
	ds_read_b128 v[210:213], v185 offset:10784
	s_waitcnt lgkmcnt(7)
	v_mfma_f32_32x32x16_bf16 v[96:111], v[220:223], v[132:135], v[96:111]
	ds_read_b128 v[220:223], v185 offset:10816
	s_waitcnt lgkmcnt(7)
	v_mfma_f32_32x32x16_bf16 v[96:111], v[224:227], v[128:131], v[96:111]
	ds_read_b128 v[224:227], v185 offset:10848
	s_waitcnt lgkmcnt(7)
	v_mfma_f32_32x32x16_bf16 v[96:111], v[2:5], v[124:127], v[96:111]
	ds_read_b128 v[2:5], v185 offset:10880
	s_waitcnt lgkmcnt(7)
	v_mfma_f32_32x32x16_bf16 v[96:111], v[6:9], v[120:123], v[96:111]
	ds_read_b128 v[6:9], v185 offset:10912
	s_waitcnt lgkmcnt(7)
	v_mfma_f32_32x32x16_bf16 v[96:111], v[194:197], v[116:119], v[96:111]
	ds_read_b128 v[194:197], v185 offset:10944
	s_waitcnt lgkmcnt(7)
	v_mfma_f32_32x32x16_bf16 v[96:111], v[202:205], v[112:115], v[96:111]
	ds_read_b128 v[202:205], v185 offset:10976
	s_waitcnt lgkmcnt(7)
	v_mfma_f32_32x32x16_bf16 v[80:95], v[206:209], v[148:151], 0
	ds_read_b128 v[206:209], v185 offset:11008
	s_waitcnt lgkmcnt(7)
	v_mfma_f32_32x32x16_bf16 v[80:95], v[210:213], v[144:147], v[80:95]
	ds_read_b128 v[210:213], v185 offset:11040
	s_waitcnt lgkmcnt(7)
	v_mfma_f32_32x32x16_bf16 v[80:95], v[220:223], v[140:143], v[80:95]
	s_waitcnt lgkmcnt(6)
	v_mfma_f32_32x32x16_bf16 v[80:95], v[224:227], v[136:139], v[80:95]
	s_waitcnt lgkmcnt(5)
	v_mfma_f32_32x32x16_bf16 v[80:95], v[2:5], v[132:135], v[80:95]
	s_waitcnt lgkmcnt(4)
	v_mfma_f32_32x32x16_bf16 v[80:95], v[6:9], v[128:131], v[80:95]
	s_waitcnt lgkmcnt(3)
	v_mfma_f32_32x32x16_bf16 v[80:95], v[194:197], v[124:127], v[80:95]
	v_max_f32_e32 v0, v97, v97
	v_max_f32_e32 v10, v96, v96
	v_max_f32_e32 v0, v10, v0
	v_max3_f32 v0, v0, v98, v99
	v_max3_f32 v0, v0, v100, v101
	v_max3_f32 v0, v0, v102, v103
	v_max3_f32 v0, v0, v104, v105
	v_max3_f32 v0, v0, v106, v107
	v_max3_f32 v0, v0, v108, v109
	v_max3_f32 v0, v0, v110, v111
	v_and_b32_e32 v3, 64, v218
	v_xor_b32_e32 v2, 32, v218
	v_add_u32_e32 v3, 64, v3
	v_cmp_lt_i32_e32 vcc, v2, v3
	s_nop 1
	v_cndmask_b32_e32 v2, v218, v2, vcc
	s_waitcnt lgkmcnt(2)
	v_mfma_f32_32x32x16_bf16 v[80:95], v[202:205], v[120:123], v[80:95]
	s_waitcnt lgkmcnt(1)
	v_mfma_f32_32x32x16_bf16 v[80:95], v[206:209], v[116:119], v[80:95]
	s_waitcnt lgkmcnt(0)
	v_mfma_f32_32x32x16_bf16 v[80:95], v[210:213], v[112:115], v[80:95]
	v_lshlrev_b32_e32 v2, 2, v2
	s_nop 10
	v_max3_f32 v0, v0, v80, v81
	v_max3_f32 v0, v0, v82, v83
	v_max3_f32 v0, v0, v84, v85
	v_max3_f32 v0, v0, v86, v87
	v_max3_f32 v0, v0, v88, v89
	v_max3_f32 v0, v0, v90, v91
	v_max3_f32 v0, v0, v92, v93
	v_max3_f32 v0, v0, v94, v95
	ds_bpermute_b32 v2, v2, v0
	s_waitcnt lgkmcnt(0)
	v_add_u32_e32 v224, 0x5000, v191
	v_add_u32_e32 v225, 0x6000, v191
	v_add_u32_e32 v226, 0x7000, v191
	v_add_u32_e32 v227, 0x8000, v191
	ds_read2_b64 v[194:197], v224 offset0:128 offset1:130
	ds_read2_b64 v[202:205], v225 offset0:160 offset1:162
	ds_read2_b64 v[206:209], v226 offset0:192 offset1:194
	ds_read2_b64 v[210:213], v227 offset0:224 offset1:226
	ds_read2_b64 v[220:223], v224 offset0:132 offset1:134
	v_max3_f32 v0, v192, v0, v2
	v_sub_f32 v4, v97, v0
	v_sub_f32 v3, v96, v0
	v_sub_f32 v5, v100, v0
	v_sub_f32_e32 v2, v192, v0
	v_exp_f32_e32 v8, v4
	v_sub_f32 v4, v98, v0
	v_exp_f32_e32 v3, v3
	v_exp_f32_e32 v9, v4
	v_sub_f32 v4, v99, v0
	v_exp_f32_e32 v11, v5
	v_exp_f32_e32 v10, v4
	v_add_f32 v4, v1, v3
	v_sub_f32 v5, v101, v0
	v_exp_f32_e32 v2, v2
	v_add_f32 v4, v4, v8
	v_exp_f32_e32 v12, v5
	v_add_f32 v4, v4, v9
	v_sub_f32 v5, v102, v0
	v_cvt_pk_bf16_f32 v8, v3, v8
	v_add_f32 v4, v4, v10
	v_exp_f32_e32 v13, v5
	v_add_f32 v4, v4, v11
	v_sub_f32 v5, v103, v0
	v_add_f32 v4, v4, v12
	v_exp_f32_e32 v14, v5
	v_add_f32 v4, v4, v13
	v_cvt_pk_bf16_f32 v9, v9, v10
	v_add_f32 v96, v4, v14
	v_sub_f32 v4, v104, v0
	v_exp_f32_e32 v97, v4
	v_sub_f32 v4, v105, v0
	v_cvt_pk_bf16_f32 v10, v11, v12
	v_exp_f32_e32 v98, v4
	v_sub_f32 v4, v106, v0
	v_cvt_pk_bf16_f32 v11, v13, v14
	v_exp_f32_e32 v99, v4
	v_sub_f32 v4, v107, v0
	v_exp_f32_e32 v100, v4
	v_sub_f32 v4, v108, v0
	v_pk_mul_f32 v[64:65], v[64:65], v[2:3] op_sel_hi:[1,0]
	v_pk_mul_f32 v[66:67], v[66:67], v[2:3] op_sel_hi:[1,0]
	v_pk_mul_f32 v[68:69], v[68:69], v[2:3] op_sel_hi:[1,0]
	s_nop 0
	v_exp_f32_e32 v101, v4
	v_sub_f32 v4, v109, v0
	v_pk_mul_f32 v[70:71], v[70:71], v[2:3] op_sel_hi:[1,0]
	v_pk_mul_f32 v[72:73], v[72:73], v[2:3] op_sel_hi:[1,0]
	s_nop 0
	v_exp_f32_e32 v102, v4
	v_sub_f32 v4, v110, v0
	v_pk_mul_f32 v[74:75], v[74:75], v[2:3] op_sel_hi:[1,0]
	v_pk_mul_f32 v[76:77], v[76:77], v[2:3] op_sel_hi:[1,0]
	v_pk_mul_f32 v[78:79], v[78:79], v[2:3] op_sel_hi:[1,0]
	s_nop 0
	v_exp_f32_e32 v103, v4
	s_waitcnt lgkmcnt(4)
	v_mfma_f32_32x32x16_bf16 v[64:79], v[194:197], v[8:11], v[64:79]
	ds_read2_b64 v[194:197], v225 offset0:164 offset1:166
	v_pk_mul_f32 v[48:49], v[48:49], v[2:3] op_sel_hi:[1,0]
	v_pk_mul_f32 v[50:51], v[50:51], v[2:3] op_sel_hi:[1,0]
	v_pk_mul_f32 v[52:53], v[52:53], v[2:3] op_sel_hi:[1,0]
	v_pk_mul_f32 v[54:55], v[54:55], v[2:3] op_sel_hi:[1,0]
	v_pk_mul_f32 v[56:57], v[56:57], v[2:3] op_sel_hi:[1,0]
	v_pk_mul_f32 v[58:59], v[58:59], v[2:3] op_sel_hi:[1,0]
	v_pk_mul_f32 v[60:61], v[60:61], v[2:3] op_sel_hi:[1,0]
	v_pk_mul_f32 v[62:63], v[62:63], v[2:3] op_sel_hi:[1,0]
	s_waitcnt lgkmcnt(4)
	v_mfma_f32_32x32x16_bf16 v[48:63], v[202:205], v[8:11], v[48:63]
	ds_read2_b64 v[202:205], v226 offset0:196 offset1:198
	v_pk_mul_f32 v[32:33], v[32:33], v[2:3] op_sel_hi:[1,0]
	v_pk_mul_f32 v[34:35], v[34:35], v[2:3] op_sel_hi:[1,0]
	v_pk_mul_f32 v[36:37], v[36:37], v[2:3] op_sel_hi:[1,0]
	v_pk_mul_f32 v[38:39], v[38:39], v[2:3] op_sel_hi:[1,0]
	v_pk_mul_f32 v[40:41], v[40:41], v[2:3] op_sel_hi:[1,0]
	v_pk_mul_f32 v[42:43], v[42:43], v[2:3] op_sel_hi:[1,0]
	v_pk_mul_f32 v[44:45], v[44:45], v[2:3] op_sel_hi:[1,0]
	v_pk_mul_f32 v[46:47], v[46:47], v[2:3] op_sel_hi:[1,0]
	v_pk_mul_f32 v[16:17], v[16:17], v[2:3] op_sel_hi:[1,0]
	v_pk_mul_f32 v[18:19], v[18:19], v[2:3] op_sel_hi:[1,0]
	v_pk_mul_f32 v[20:21], v[20:21], v[2:3] op_sel_hi:[1,0]
	s_waitcnt lgkmcnt(4)
	v_mfma_f32_32x32x16_bf16 v[32:47], v[206:209], v[8:11], v[32:47]
	ds_read2_b64 v[206:209], v227 offset0:228 offset1:230
	v_pk_mul_f32 v[22:23], v[22:23], v[2:3] op_sel_hi:[1,0]
	v_pk_mul_f32 v[24:25], v[24:25], v[2:3] op_sel_hi:[1,0]
	v_pk_mul_f32 v[26:27], v[26:27], v[2:3] op_sel_hi:[1,0]
	v_pk_mul_f32 v[28:29], v[28:29], v[2:3] op_sel_hi:[1,0]
	v_pk_mul_f32 v[30:31], v[30:31], v[2:3] op_sel_hi:[1,0]
	v_mov_b32_e32 v192, v0
	s_waitcnt lgkmcnt(4)
	v_mfma_f32_32x32x16_bf16 v[16:31], v[210:213], v[8:11], v[16:31]
	ds_read2_b64 v[210:213], v224 offset0:136 offset1:138
	v_sub_f32 v8, v111, v0
	v_cvt_pk_bf16_f32 v9, v99, v100
	v_exp_f32_e32 v107, v8
	v_cvt_pk_bf16_f32 v8, v97, v98
	v_cvt_pk_bf16_f32 v10, v101, v102
	v_cvt_pk_bf16_f32 v11, v103, v107
	s_nop 0
	s_waitcnt lgkmcnt(4)
	v_mfma_f32_32x32x16_bf16 v[64:79], v[220:223], v[8:11], v[64:79]
	ds_read2_b64 v[220:223], v225 offset0:168 offset1:170
	v_add_f32 v4, v96, v97
	s_nop 0
	v_add_f32 v4, v4, v98
	s_nop 0
	v_add_f32 v4, v4, v99
	s_nop 0
	v_add_f32 v96, v4, v100
	v_sub_f32 v4, v80, v0
	s_waitcnt lgkmcnt(4)
	v_mfma_f32_32x32x16_bf16 v[48:63], v[194:197], v[8:11], v[48:63]
	ds_read2_b64 v[194:197], v226 offset0:200 offset1:202
	v_exp_f32_e32 v80, v4
	v_sub_f32 v12, v81, v0
	s_nop 0
	v_exp_f32_e32 v81, v12
	v_sub_f32 v12, v82, v0
	s_nop 0
	v_exp_f32_e32 v82, v12
	v_sub_f32 v12, v83, v0
	s_waitcnt lgkmcnt(4)
	v_mfma_f32_32x32x16_bf16 v[32:47], v[202:205], v[8:11], v[32:47]
	ds_read2_b64 v[202:205], v227 offset0:232 offset1:234
	v_exp_f32_e32 v83, v12
	v_sub_f32 v4, v84, v0
	s_nop 0
	v_exp_f32_e32 v84, v4
	v_sub_f32 v4, v85, v0
	s_nop 0
	v_exp_f32_e32 v85, v4
	v_sub_f32 v4, v86, v0
	s_waitcnt lgkmcnt(4)
	v_mfma_f32_32x32x16_bf16 v[16:31], v[206:209], v[8:11], v[16:31]
	ds_read2_b64 v[206:209], v224 offset0:140 offset1:142
	v_exp_f32_e32 v86, v4
	v_sub_f32 v8, v87, v0
	v_exp_f32_e32 v87, v8
	v_cvt_pk_bf16_f32 v8, v80, v81
	v_cvt_pk_bf16_f32 v9, v82, v83
	v_cvt_pk_bf16_f32 v10, v84, v85
	v_cvt_pk_bf16_f32 v11, v86, v87
	s_nop 0
	s_waitcnt lgkmcnt(4)
	v_mfma_f32_32x32x16_bf16 v[64:79], v[210:213], v[8:11], v[64:79]
	ds_read2_b64 v[210:213], v225 offset0:172 offset1:174
	v_add_f32 v4, v96, v101
	s_nop 0
	v_add_f32 v4, v4, v102
	s_nop 0
	v_add_f32 v4, v4, v103
	s_nop 0
	v_add_f32 v96, v4, v107
	v_sub_f32 v4, v88, v0
	s_waitcnt lgkmcnt(4)
	v_mfma_f32_32x32x16_bf16 v[48:63], v[220:223], v[8:11], v[48:63]
	ds_read2_b64 v[220:223], v226 offset0:204 offset1:206
	v_exp_f32_e32 v88, v4
	v_sub_f32 v12, v89, v0
	s_nop 0
	v_exp_f32_e32 v89, v12
	v_sub_f32 v12, v90, v0
	s_nop 0
	v_exp_f32_e32 v90, v12
	v_sub_f32 v12, v91, v0
	s_waitcnt lgkmcnt(4)
	v_mfma_f32_32x32x16_bf16 v[32:47], v[194:197], v[8:11], v[32:47]
	ds_read2_b64 v[194:197], v227 offset0:236 offset1:238
	v_exp_f32_e32 v91, v12
	v_sub_f32 v4, v92, v0
	s_nop 0
	v_exp_f32_e32 v92, v4
	v_sub_f32 v4, v93, v0
	s_nop 0
	v_exp_f32_e32 v93, v4
	v_sub_f32 v4, v94, v0
	s_waitcnt lgkmcnt(4)
	v_mfma_f32_32x32x16_bf16 v[16:31], v[202:205], v[8:11], v[16:31]
	v_exp_f32_e32 v94, v4
	v_sub_f32 v8, v95, v0
	v_cvt_pk_bf16_f32 v9, v90, v91
	v_exp_f32_e32 v95, v8
	v_cvt_pk_bf16_f32 v8, v88, v89
	v_cvt_pk_bf16_f32 v10, v92, v93
	v_add_f32 v3, v96, v80
	v_cvt_pk_bf16_f32 v11, v94, v95
	v_add_f32 v3, v3, v81
	s_nop 0
	v_add_f32 v3, v3, v82
	s_waitcnt lgkmcnt(3)
	v_mfma_f32_32x32x16_bf16 v[64:79], v[206:209], v[8:11], v[64:79]
	v_add_f32 v3, v3, v83
	s_nop 0
	v_add_f32 v3, v3, v84
	s_nop 0
	v_add_f32 v3, v3, v85
	s_waitcnt lgkmcnt(2)
	v_mfma_f32_32x32x16_bf16 v[48:63], v[210:213], v[8:11], v[48:63]
	v_add_f32 v3, v3, v86
	s_nop 0
	v_add_f32 v3, v3, v87
	s_nop 0
	v_add_f32 v3, v3, v88
	s_nop 0
	v_add_f32 v3, v3, v89
	s_waitcnt lgkmcnt(1)
	v_mfma_f32_32x32x16_bf16 v[32:47], v[220:223], v[8:11], v[32:47]
	v_add_f32 v3, v3, v90
	s_nop 0
	v_add_f32 v3, v3, v91
	s_nop 0
	v_add_f32 v3, v3, v92
	s_nop 0
	v_add_f32 v3, v3, v93
	s_waitcnt lgkmcnt(0)
	v_mfma_f32_32x32x16_bf16 v[16:31], v[194:197], v[8:11], v[16:31]
	v_add_f32 v3, v3, v94
	s_nop 0
	v_add_f32 v3, v3, v95
	s_nop 0
	v_fmac_f32_e32 v3, v184, v2
	v_mov_b32_e32 v184, v3
	s_branch .LBB0_587
